# v58 + GEMM K-loop MFMA segments start with bare MFMAs: the duplicate post-barrier s_waitcnt lgkmcnt(0) removed (the drain before the barrier is kept)
# baseline (speedup 1.0000x reference)
.LBB0_64:
	s_add_i32 s33, s42, 2
	s_add_u32 s46, s40, 0x80
	s_addc_u32 s43, s41, 0
	s_add_i32 s80, 0, 0x10000
	s_cmp_eq_u32 s84, s42
	s_cselect_b32 s43, s1, s43
	s_cselect_b32 s42, s0, s46
	s_cselect_b32 s47, s75, vcc_hi
	s_cselect_b32 s46, s74, vcc_lo
	s_add_i32 s5, 0, 0x14000
	ds_read_b128 v[128:131], v249
	ds_read_b128 v[132:135], v249 offset:1024
	ds_read_b128 v[136:139], v249 offset:2048
	ds_read_b128 v[140:143], v249 offset:3072
	ds_read_b128 v[144:147], v249 offset:16384
	ds_read_b128 v[148:151], v249 offset:17408
	ds_read_b128 v[152:155], v249 offset:18432
	ds_read_b128 v[166:169], v249 offset:19456
	v_lshl_add_u64 v[182:183], s[40:41], 0, v[162:163]
	s_add_i32 m0, s28, 0xc000
	ds_read_b128 v[170:173], v188
	ds_read_b128 v[174:177], v188 offset:1024
	ds_read_b128 v[178:181], v188 offset:2048
	ds_read_b128 v[214:217], v188 offset:3072
	ds_read_b128 v[218:221], v188 offset:4096
	ds_read_b128 v[222:225], v188 offset:5120
	ds_read_b128 v[226:229], v188 offset:6144
	ds_read_b128 v[230:233], v188 offset:7168
	global_load_lds_dwordx4 v[182:183], off
	v_lshl_add_u64 v[182:183], s[40:41], 0, v[164:165]
	s_add_i32 m0, s28, 0xe000
	s_nop 0
	global_load_lds_dwordx4 v[182:183], off
	s_waitcnt vmcnt(8)
	s_waitcnt lgkmcnt(0)
	s_barrier
	v_mfma_f32_16x16x32_bf16 v[124:127], v[128:131], v[170:173], v[124:127]
	v_mfma_f32_16x16x32_bf16 v[120:123], v[136:139], v[170:173], v[120:123]
	v_mfma_f32_16x16x32_bf16 v[108:111], v[128:131], v[178:181], v[108:111]
	v_mfma_f32_16x16x32_bf16 v[104:107], v[136:139], v[178:181], v[104:107]
	v_mfma_f32_16x16x32_bf16 v[92:95], v[128:131], v[218:221], v[92:95]
	v_mfma_f32_16x16x32_bf16 v[88:91], v[136:139], v[218:221], v[88:91]
	v_mfma_f32_16x16x32_bf16 v[76:79], v[128:131], v[226:229], v[76:79]
	v_mfma_f32_16x16x32_bf16 v[72:75], v[136:139], v[226:229], v[72:75]
	v_mfma_f32_16x16x32_bf16 v[124:127], v[132:135], v[174:177], v[124:127]
	v_mfma_f32_16x16x32_bf16 v[120:123], v[140:143], v[174:177], v[120:123]
	v_mfma_f32_16x16x32_bf16 v[108:111], v[132:135], v[214:217], v[108:111]
	v_mfma_f32_16x16x32_bf16 v[104:107], v[140:143], v[214:217], v[104:107]
	v_mfma_f32_16x16x32_bf16 v[92:95], v[132:135], v[222:225], v[92:95]
	v_mfma_f32_16x16x32_bf16 v[88:91], v[140:143], v[222:225], v[88:91]
	v_mfma_f32_16x16x32_bf16 v[76:79], v[132:135], v[230:233], v[76:79]
	v_mfma_f32_16x16x32_bf16 v[72:75], v[140:143], v[230:233], v[72:75]
	v_mfma_f32_16x16x32_bf16 v[116:119], v[144:147], v[170:173], v[116:119]
	v_mfma_f32_16x16x32_bf16 v[112:115], v[152:155], v[170:173], v[112:115]
	v_mfma_f32_16x16x32_bf16 v[100:103], v[144:147], v[178:181], v[100:103]
	v_mfma_f32_16x16x32_bf16 v[96:99], v[152:155], v[178:181], v[96:99]
	v_mfma_f32_16x16x32_bf16 v[84:87], v[144:147], v[218:221], v[84:87]
	v_mfma_f32_16x16x32_bf16 v[80:83], v[152:155], v[218:221], v[80:83]
	v_mfma_f32_16x16x32_bf16 v[68:71], v[144:147], v[226:229], v[68:71]
	v_mfma_f32_16x16x32_bf16 v[64:67], v[152:155], v[226:229], v[64:67]
	v_mfma_f32_16x16x32_bf16 v[116:119], v[148:151], v[174:177], v[116:119]
	v_mfma_f32_16x16x32_bf16 v[112:115], v[166:169], v[174:177], v[112:115]
	v_mfma_f32_16x16x32_bf16 v[100:103], v[148:151], v[214:217], v[100:103]
	v_mfma_f32_16x16x32_bf16 v[96:99], v[166:169], v[214:217], v[96:99]
	v_mfma_f32_16x16x32_bf16 v[84:87], v[148:151], v[222:225], v[84:87]
	v_mfma_f32_16x16x32_bf16 v[80:83], v[166:169], v[222:225], v[80:83]
	v_mfma_f32_16x16x32_bf16 v[68:71], v[148:151], v[230:233], v[68:71]
	v_mfma_f32_16x16x32_bf16 v[64:67], v[166:169], v[230:233], v[64:67]
	s_barrier
	s_add_i32 s80, s80, s27
	v_lshl_add_u64 v[182:183], s[46:47], 0, v[192:193]
	s_mov_b32 m0, s80
	ds_read_b128 v[170:173], v188 offset:16384
	ds_read_b128 v[174:177], v188 offset:17408
	ds_read_b128 v[178:181], v188 offset:18432
	ds_read_b128 v[214:217], v188 offset:19456
	ds_read_b128 v[218:221], v188 offset:20480
	ds_read_b128 v[222:225], v188 offset:21504
	ds_read_b128 v[226:229], v188 offset:22528
	ds_read_b128 v[230:233], v188 offset:23552
	global_load_lds_dwordx4 v[182:183], off
	s_add_i32 m0, s80, 0x2000
	v_lshl_add_u64 v[190:191], s[46:47], 0, v[160:161]
	s_add_u32 s46, s46, s30
	s_addc_u32 s47, s47, 0
	s_add_i32 s5, s5, s27
	global_load_lds_dwordx4 v[190:191], off
	v_lshl_add_u64 v[200:201], s[46:47], 0, v[192:193]
	s_mov_b32 m0, s5
	v_lshl_add_u64 v[234:235], s[46:47], 0, v[160:161]
	global_load_lds_dwordx4 v[200:201], off
	s_add_i32 m0, s5, 0x2000
	v_lshl_add_u64 v[236:237], s[42:43], 0, v[156:157]
	global_load_lds_dwordx4 v[234:235], off
	s_mov_b32 m0, s28
	v_lshl_add_u64 v[238:239], s[42:43], 0, v[158:159]
	global_load_lds_dwordx4 v[236:237], off
	s_mov_b32 m0, s69
	s_nop 0
	global_load_lds_dwordx4 v[238:239], off
	s_waitcnt vmcnt(8)
	s_waitcnt lgkmcnt(0)
	s_barrier
	v_mfma_f32_16x16x32_bf16 v[60:63], v[128:131], v[170:173], v[60:63]
	v_mfma_f32_16x16x32_bf16 v[56:59], v[136:139], v[170:173], v[56:59]
	v_mfma_f32_16x16x32_bf16 v[44:47], v[128:131], v[178:181], v[44:47]
	v_mfma_f32_16x16x32_bf16 v[40:43], v[136:139], v[178:181], v[40:43]
	v_mfma_f32_16x16x32_bf16 v[28:31], v[128:131], v[218:221], v[28:31]
	v_mfma_f32_16x16x32_bf16 v[24:27], v[136:139], v[218:221], v[24:27]
	v_mfma_f32_16x16x32_bf16 v[12:15], v[128:131], v[226:229], v[12:15]
	v_mfma_f32_16x16x32_bf16 v[8:11], v[136:139], v[226:229], v[8:11]
	v_mfma_f32_16x16x32_bf16 v[60:63], v[132:135], v[174:177], v[60:63]
	v_mfma_f32_16x16x32_bf16 v[56:59], v[140:143], v[174:177], v[56:59]
	v_mfma_f32_16x16x32_bf16 v[44:47], v[132:135], v[214:217], v[44:47]
	v_mfma_f32_16x16x32_bf16 v[40:43], v[140:143], v[214:217], v[40:43]
	v_mfma_f32_16x16x32_bf16 v[28:31], v[132:135], v[222:225], v[28:31]
	v_mfma_f32_16x16x32_bf16 v[24:27], v[140:143], v[222:225], v[24:27]
	v_mfma_f32_16x16x32_bf16 v[12:15], v[132:135], v[230:233], v[12:15]
	v_mfma_f32_16x16x32_bf16 v[8:11], v[140:143], v[230:233], v[8:11]
	v_mfma_f32_16x16x32_bf16 v[52:55], v[144:147], v[170:173], v[52:55]
	v_mfma_f32_16x16x32_bf16 v[48:51], v[152:155], v[170:173], v[48:51]
	v_mfma_f32_16x16x32_bf16 v[36:39], v[144:147], v[178:181], v[36:39]
	v_mfma_f32_16x16x32_bf16 v[32:35], v[152:155], v[178:181], v[32:35]
	v_mfma_f32_16x16x32_bf16 v[20:23], v[144:147], v[218:221], v[20:23]
	v_mfma_f32_16x16x32_bf16 v[16:19], v[152:155], v[218:221], v[16:19]
	v_mfma_f32_16x16x32_bf16 v[4:7], v[144:147], v[226:229], v[4:7]
	v_mfma_f32_16x16x32_bf16 v[0:3], v[152:155], v[226:229], v[0:3]
	v_mfma_f32_16x16x32_bf16 v[52:55], v[148:151], v[174:177], v[52:55]
	v_mfma_f32_16x16x32_bf16 v[48:51], v[166:169], v[174:177], v[48:51]
	v_mfma_f32_16x16x32_bf16 v[36:39], v[148:151], v[214:217], v[36:39]
	v_mfma_f32_16x16x32_bf16 v[32:35], v[166:169], v[214:217], v[32:35]
	v_mfma_f32_16x16x32_bf16 v[20:23], v[148:151], v[222:225], v[20:23]
	v_mfma_f32_16x16x32_bf16 v[16:19], v[166:169], v[222:225], v[16:19]
	v_mfma_f32_16x16x32_bf16 v[4:7], v[148:151], v[230:233], v[4:7]
	v_mfma_f32_16x16x32_bf16 v[0:3], v[166:169], v[230:233], v[0:3]
	s_barrier
.Lmy_sp3:
	s_add_i32 s5, 0, 0x18000
	s_add_i32 s46, 0, 0x1c000
	ds_read_b128 v[128:131], v249 offset:32768
	ds_read_b128 v[132:135], v249 offset:33792
	ds_read_b128 v[136:139], v249 offset:34816
	ds_read_b128 v[140:143], v249 offset:35840
	ds_read_b128 v[144:147], v249 offset:49152
	ds_read_b128 v[148:151], v249 offset:50176
	ds_read_b128 v[152:155], v249 offset:51200
	ds_read_b128 v[166:169], v249 offset:52224
	s_add_u32 s42, s42, s30
	s_addc_u32 s43, s43, 0
	s_mov_b32 m0, s72
	v_lshl_add_u64 v[240:241], s[42:43], 0, v[156:157]
	ds_read_b128 v[170:173], v188 offset:32768
	ds_read_b128 v[174:177], v188 offset:33792
	ds_read_b128 v[178:181], v188 offset:34816
	ds_read_b128 v[214:217], v188 offset:35840
	ds_read_b128 v[218:221], v188 offset:36864
	ds_read_b128 v[222:225], v188 offset:37888
	ds_read_b128 v[226:229], v188 offset:38912
	ds_read_b128 v[230:233], v188 offset:39936
	global_load_lds_dwordx4 v[240:241], off
	v_lshl_add_u64 v[240:241], s[42:43], 0, v[158:159]
	s_mov_b32 m0, s76
	s_nop 0
	global_load_lds_dwordx4 v[240:241], off
	s_waitcnt vmcnt(8)
	s_waitcnt lgkmcnt(0)
	s_barrier
	v_mfma_f32_16x16x32_bf16 v[124:127], v[128:131], v[170:173], v[124:127]
	v_mfma_f32_16x16x32_bf16 v[120:123], v[136:139], v[170:173], v[120:123]
	v_mfma_f32_16x16x32_bf16 v[108:111], v[128:131], v[178:181], v[108:111]
	v_mfma_f32_16x16x32_bf16 v[104:107], v[136:139], v[178:181], v[104:107]
	v_mfma_f32_16x16x32_bf16 v[92:95], v[128:131], v[218:221], v[92:95]
	v_mfma_f32_16x16x32_bf16 v[88:91], v[136:139], v[218:221], v[88:91]
	v_mfma_f32_16x16x32_bf16 v[76:79], v[128:131], v[226:229], v[76:79]
	v_mfma_f32_16x16x32_bf16 v[72:75], v[136:139], v[226:229], v[72:75]
	v_mfma_f32_16x16x32_bf16 v[124:127], v[132:135], v[174:177], v[124:127]
	v_mfma_f32_16x16x32_bf16 v[120:123], v[140:143], v[174:177], v[120:123]
	v_mfma_f32_16x16x32_bf16 v[108:111], v[132:135], v[214:217], v[108:111]
	v_mfma_f32_16x16x32_bf16 v[104:107], v[140:143], v[214:217], v[104:107]
	v_mfma_f32_16x16x32_bf16 v[92:95], v[132:135], v[222:225], v[92:95]
	v_mfma_f32_16x16x32_bf16 v[88:91], v[140:143], v[222:225], v[88:91]
	v_mfma_f32_16x16x32_bf16 v[76:79], v[132:135], v[230:233], v[76:79]
	v_mfma_f32_16x16x32_bf16 v[72:75], v[140:143], v[230:233], v[72:75]
	v_mfma_f32_16x16x32_bf16 v[116:119], v[144:147], v[170:173], v[116:119]
	v_mfma_f32_16x16x32_bf16 v[112:115], v[152:155], v[170:173], v[112:115]
	v_mfma_f32_16x16x32_bf16 v[100:103], v[144:147], v[178:181], v[100:103]
	v_mfma_f32_16x16x32_bf16 v[96:99], v[152:155], v[178:181], v[96:99]
	v_mfma_f32_16x16x32_bf16 v[84:87], v[144:147], v[218:221], v[84:87]
	v_mfma_f32_16x16x32_bf16 v[80:83], v[152:155], v[218:221], v[80:83]
	v_mfma_f32_16x16x32_bf16 v[68:71], v[144:147], v[226:229], v[68:71]
	v_mfma_f32_16x16x32_bf16 v[64:67], v[152:155], v[226:229], v[64:67]
	v_mfma_f32_16x16x32_bf16 v[116:119], v[148:151], v[174:177], v[116:119]
	v_mfma_f32_16x16x32_bf16 v[112:115], v[166:169], v[174:177], v[112:115]
	v_mfma_f32_16x16x32_bf16 v[100:103], v[148:151], v[214:217], v[100:103]
	v_mfma_f32_16x16x32_bf16 v[96:99], v[166:169], v[214:217], v[96:99]
	v_mfma_f32_16x16x32_bf16 v[84:87], v[148:151], v[222:225], v[84:87]
	v_mfma_f32_16x16x32_bf16 v[80:83], v[166:169], v[222:225], v[80:83]
	v_mfma_f32_16x16x32_bf16 v[68:71], v[148:151], v[230:233], v[68:71]
	v_mfma_f32_16x16x32_bf16 v[64:67], v[166:169], v[230:233], v[64:67]
	s_barrier
	s_add_i32 s5, s5, s27
	v_lshl_add_u64 v[182:183], v[182:183], 0, s[70:71]
	s_mov_b32 m0, s5
	ds_read_b128 v[170:173], v188 offset:49152
	ds_read_b128 v[174:177], v188 offset:50176
	ds_read_b128 v[178:181], v188 offset:51200
	ds_read_b128 v[214:217], v188 offset:52224
	ds_read_b128 v[218:221], v188 offset:53248
	ds_read_b128 v[222:225], v188 offset:54272
	ds_read_b128 v[226:229], v188 offset:55296
	ds_read_b128 v[230:233], v188 offset:56320
	global_load_lds_dwordx4 v[182:183], off
	v_lshl_add_u64 v[182:183], v[190:191], 0, s[70:71]
	s_add_i32 m0, s5, 0x2000
	s_add_i32 s5, s46, s27
	global_load_lds_dwordx4 v[182:183], off
	v_lshl_add_u64 v[182:183], v[200:201], 0, s[70:71]
	s_mov_b32 m0, s5
	s_nop 0
	global_load_lds_dwordx4 v[182:183], off
	v_lshl_add_u64 v[182:183], v[234:235], 0, s[70:71]
	s_add_i32 m0, s5, 0x2000
	s_nop 0
	global_load_lds_dwordx4 v[182:183], off
	v_lshl_add_u64 v[182:183], v[236:237], 0, s[70:71]
	s_mov_b32 m0, s81
	s_nop 0
	global_load_lds_dwordx4 v[182:183], off
	v_lshl_add_u64 v[182:183], v[238:239], 0, s[70:71]
	s_mov_b32 m0, s82
	s_nop 0
	global_load_lds_dwordx4 v[182:183], off
	s_waitcnt vmcnt(8)
	s_waitcnt lgkmcnt(0)
	s_barrier
	v_mfma_f32_16x16x32_bf16 v[60:63], v[128:131], v[170:173], v[60:63]
	v_mfma_f32_16x16x32_bf16 v[56:59], v[136:139], v[170:173], v[56:59]
	v_mfma_f32_16x16x32_bf16 v[44:47], v[128:131], v[178:181], v[44:47]
	v_mfma_f32_16x16x32_bf16 v[40:43], v[136:139], v[178:181], v[40:43]
	v_mfma_f32_16x16x32_bf16 v[28:31], v[128:131], v[218:221], v[28:31]
	v_mfma_f32_16x16x32_bf16 v[24:27], v[136:139], v[218:221], v[24:27]
	v_mfma_f32_16x16x32_bf16 v[12:15], v[128:131], v[226:229], v[12:15]
	v_mfma_f32_16x16x32_bf16 v[8:11], v[136:139], v[226:229], v[8:11]
	v_mfma_f32_16x16x32_bf16 v[60:63], v[132:135], v[174:177], v[60:63]
	v_mfma_f32_16x16x32_bf16 v[56:59], v[140:143], v[174:177], v[56:59]
	v_mfma_f32_16x16x32_bf16 v[44:47], v[132:135], v[214:217], v[44:47]
	v_mfma_f32_16x16x32_bf16 v[40:43], v[140:143], v[214:217], v[40:43]
	v_mfma_f32_16x16x32_bf16 v[28:31], v[132:135], v[222:225], v[28:31]
	v_mfma_f32_16x16x32_bf16 v[24:27], v[140:143], v[222:225], v[24:27]
	v_mfma_f32_16x16x32_bf16 v[12:15], v[132:135], v[230:233], v[12:15]
	v_mfma_f32_16x16x32_bf16 v[8:11], v[140:143], v[230:233], v[8:11]
	v_mfma_f32_16x16x32_bf16 v[52:55], v[144:147], v[170:173], v[52:55]
	v_mfma_f32_16x16x32_bf16 v[48:51], v[152:155], v[170:173], v[48:51]
	v_mfma_f32_16x16x32_bf16 v[36:39], v[144:147], v[178:181], v[36:39]
	v_mfma_f32_16x16x32_bf16 v[32:35], v[152:155], v[178:181], v[32:35]
	v_mfma_f32_16x16x32_bf16 v[20:23], v[144:147], v[218:221], v[20:23]
	v_mfma_f32_16x16x32_bf16 v[16:19], v[152:155], v[218:221], v[16:19]
	v_mfma_f32_16x16x32_bf16 v[4:7], v[144:147], v[226:229], v[4:7]
	v_mfma_f32_16x16x32_bf16 v[0:3], v[152:155], v[226:229], v[0:3]
	v_mfma_f32_16x16x32_bf16 v[52:55], v[148:151], v[174:177], v[52:55]
	v_mfma_f32_16x16x32_bf16 v[48:51], v[166:169], v[174:177], v[48:51]
	v_mfma_f32_16x16x32_bf16 v[36:39], v[148:151], v[214:217], v[36:39]
	v_mfma_f32_16x16x32_bf16 v[32:35], v[166:169], v[214:217], v[32:35]
	v_mfma_f32_16x16x32_bf16 v[20:23], v[148:151], v[222:225], v[20:23]
	v_mfma_f32_16x16x32_bf16 v[16:19], v[166:169], v[222:225], v[16:19]
	v_mfma_f32_16x16x32_bf16 v[4:7], v[148:151], v[230:233], v[4:7]
	v_mfma_f32_16x16x32_bf16 v[0:3], v[166:169], v[230:233], v[0:3]
	s_barrier
	s_add_u32 s40, s40, 0x100
	s_addc_u32 s41, s41, 0
	s_add_u32 vcc_lo, vcc_lo, 0x100
	s_addc_u32 vcc_hi, vcc_hi, 0
	s_cmp_ge_u32 s33, s78
	s_mov_b32 s42, s33
	s_cbranch_scc0 .LBB0_64
	s_and_b64 vcc, exec, s[66:67]
	s_cbranch_vccz .LBB0_67
	s_barrier

.Lmy_peel:
	s_add_i32 s33, s42, 2
	s_add_u32 s46, s40, 0x80
	s_addc_u32 s43, s41, 0
	s_add_i32 s80, 0, 0x10000
	s_cmp_eq_u32 s84, s42
	s_cselect_b32 s43, s1, s43
	s_cselect_b32 s42, s0, s46
	s_cselect_b32 s47, s75, vcc_hi
	s_cselect_b32 s46, s74, vcc_lo
	s_add_i32 s5, 0, 0x14000
	ds_read_b128 v[128:131], v249
	ds_read_b128 v[132:135], v249 offset:1024
	ds_read_b128 v[136:139], v249 offset:2048
	ds_read_b128 v[140:143], v249 offset:3072
	ds_read_b128 v[144:147], v249 offset:16384
	ds_read_b128 v[148:151], v249 offset:17408
	ds_read_b128 v[152:155], v249 offset:18432
	ds_read_b128 v[166:169], v249 offset:19456
	v_lshl_add_u64 v[182:183], s[40:41], 0, v[162:163]
	s_add_i32 m0, s28, 0xc000
	ds_read_b128 v[170:173], v188
	ds_read_b128 v[174:177], v188 offset:1024
	ds_read_b128 v[178:181], v188 offset:2048
	ds_read_b128 v[214:217], v188 offset:3072
	ds_read_b128 v[218:221], v188 offset:4096
	ds_read_b128 v[222:225], v188 offset:5120
	ds_read_b128 v[226:229], v188 offset:6144
	ds_read_b128 v[230:233], v188 offset:7168
	global_load_lds_dwordx4 v[182:183], off
	v_lshl_add_u64 v[182:183], s[40:41], 0, v[164:165]
	s_add_i32 m0, s28, 0xe000
	s_nop 0
	global_load_lds_dwordx4 v[182:183], off
	s_waitcnt vmcnt(24)
	s_waitcnt lgkmcnt(0)
	s_barrier
	v_mfma_f32_16x16x32_bf16 v[124:127], v[128:131], v[170:173], 0
	v_mfma_f32_16x16x32_bf16 v[120:123], v[136:139], v[170:173], 0
	v_mfma_f32_16x16x32_bf16 v[108:111], v[128:131], v[178:181], 0
	v_mfma_f32_16x16x32_bf16 v[104:107], v[136:139], v[178:181], 0
	v_mfma_f32_16x16x32_bf16 v[92:95], v[128:131], v[218:221], 0
	v_mfma_f32_16x16x32_bf16 v[88:91], v[136:139], v[218:221], 0
	v_mfma_f32_16x16x32_bf16 v[76:79], v[128:131], v[226:229], 0
	v_mfma_f32_16x16x32_bf16 v[72:75], v[136:139], v[226:229], 0
	v_mfma_f32_16x16x32_bf16 v[124:127], v[132:135], v[174:177], v[124:127]
	v_mfma_f32_16x16x32_bf16 v[120:123], v[140:143], v[174:177], v[120:123]
	v_mfma_f32_16x16x32_bf16 v[108:111], v[132:135], v[214:217], v[108:111]
	v_mfma_f32_16x16x32_bf16 v[104:107], v[140:143], v[214:217], v[104:107]
	v_mfma_f32_16x16x32_bf16 v[92:95], v[132:135], v[222:225], v[92:95]
	v_mfma_f32_16x16x32_bf16 v[88:91], v[140:143], v[222:225], v[88:91]
	v_mfma_f32_16x16x32_bf16 v[76:79], v[132:135], v[230:233], v[76:79]
	v_mfma_f32_16x16x32_bf16 v[72:75], v[140:143], v[230:233], v[72:75]
	v_mfma_f32_16x16x32_bf16 v[116:119], v[144:147], v[170:173], 0
	v_mfma_f32_16x16x32_bf16 v[112:115], v[152:155], v[170:173], 0
	v_mfma_f32_16x16x32_bf16 v[100:103], v[144:147], v[178:181], 0
	v_mfma_f32_16x16x32_bf16 v[96:99], v[152:155], v[178:181], 0
	v_mfma_f32_16x16x32_bf16 v[84:87], v[144:147], v[218:221], 0
	v_mfma_f32_16x16x32_bf16 v[80:83], v[152:155], v[218:221], 0
	v_mfma_f32_16x16x32_bf16 v[68:71], v[144:147], v[226:229], 0
	v_mfma_f32_16x16x32_bf16 v[64:67], v[152:155], v[226:229], 0
	v_mfma_f32_16x16x32_bf16 v[116:119], v[148:151], v[174:177], v[116:119]
	v_mfma_f32_16x16x32_bf16 v[112:115], v[166:169], v[174:177], v[112:115]
	v_mfma_f32_16x16x32_bf16 v[100:103], v[148:151], v[214:217], v[100:103]
	v_mfma_f32_16x16x32_bf16 v[96:99], v[166:169], v[214:217], v[96:99]
	v_mfma_f32_16x16x32_bf16 v[84:87], v[148:151], v[222:225], v[84:87]
	v_mfma_f32_16x16x32_bf16 v[80:83], v[166:169], v[222:225], v[80:83]
	v_mfma_f32_16x16x32_bf16 v[68:71], v[148:151], v[230:233], v[68:71]
	v_mfma_f32_16x16x32_bf16 v[64:67], v[166:169], v[230:233], v[64:67]
	s_barrier
	s_add_i32 s80, s80, s27
	v_lshl_add_u64 v[182:183], s[46:47], 0, v[192:193]
	s_mov_b32 m0, s80
	ds_read_b128 v[170:173], v188 offset:16384
	ds_read_b128 v[174:177], v188 offset:17408
	ds_read_b128 v[178:181], v188 offset:18432
	ds_read_b128 v[214:217], v188 offset:19456
	ds_read_b128 v[218:221], v188 offset:20480
	ds_read_b128 v[222:225], v188 offset:21504
	ds_read_b128 v[226:229], v188 offset:22528
	ds_read_b128 v[230:233], v188 offset:23552
	global_load_lds_dwordx4 v[182:183], off
	s_add_i32 m0, s80, 0x2000
	v_lshl_add_u64 v[190:191], s[46:47], 0, v[160:161]
	s_add_u32 s46, s46, s30
	s_addc_u32 s47, s47, 0
	s_add_i32 s5, s5, s27
	global_load_lds_dwordx4 v[190:191], off
	v_lshl_add_u64 v[200:201], s[46:47], 0, v[192:193]
	s_mov_b32 m0, s5
	v_lshl_add_u64 v[234:235], s[46:47], 0, v[160:161]
	global_load_lds_dwordx4 v[200:201], off
	s_add_i32 m0, s5, 0x2000
	v_lshl_add_u64 v[236:237], s[42:43], 0, v[156:157]
	global_load_lds_dwordx4 v[234:235], off
	s_mov_b32 m0, s28
	v_lshl_add_u64 v[238:239], s[42:43], 0, v[158:159]
	global_load_lds_dwordx4 v[236:237], off
	s_mov_b32 m0, s69
	s_nop 0
	global_load_lds_dwordx4 v[238:239], off
	s_waitcnt vmcnt(24)
	s_waitcnt lgkmcnt(0)
	s_barrier
	v_mfma_f32_16x16x32_bf16 v[60:63], v[128:131], v[170:173], 0
	v_mfma_f32_16x16x32_bf16 v[56:59], v[136:139], v[170:173], 0
	v_mfma_f32_16x16x32_bf16 v[44:47], v[128:131], v[178:181], 0
	v_mfma_f32_16x16x32_bf16 v[40:43], v[136:139], v[178:181], 0
	v_mfma_f32_16x16x32_bf16 v[28:31], v[128:131], v[218:221], 0
	v_mfma_f32_16x16x32_bf16 v[24:27], v[136:139], v[218:221], 0
	v_mfma_f32_16x16x32_bf16 v[12:15], v[128:131], v[226:229], 0
	v_mfma_f32_16x16x32_bf16 v[8:11], v[136:139], v[226:229], 0
	v_mfma_f32_16x16x32_bf16 v[60:63], v[132:135], v[174:177], v[60:63]
	v_mfma_f32_16x16x32_bf16 v[56:59], v[140:143], v[174:177], v[56:59]
	v_mfma_f32_16x16x32_bf16 v[44:47], v[132:135], v[214:217], v[44:47]
	v_mfma_f32_16x16x32_bf16 v[40:43], v[140:143], v[214:217], v[40:43]
	v_mfma_f32_16x16x32_bf16 v[28:31], v[132:135], v[222:225], v[28:31]
	v_mfma_f32_16x16x32_bf16 v[24:27], v[140:143], v[222:225], v[24:27]
	v_mfma_f32_16x16x32_bf16 v[12:15], v[132:135], v[230:233], v[12:15]
	v_mfma_f32_16x16x32_bf16 v[8:11], v[140:143], v[230:233], v[8:11]
	v_mfma_f32_16x16x32_bf16 v[52:55], v[144:147], v[170:173], 0
	v_mfma_f32_16x16x32_bf16 v[48:51], v[152:155], v[170:173], 0
	v_mfma_f32_16x16x32_bf16 v[36:39], v[144:147], v[178:181], 0
	v_mfma_f32_16x16x32_bf16 v[32:35], v[152:155], v[178:181], 0
	v_mfma_f32_16x16x32_bf16 v[20:23], v[144:147], v[218:221], 0
	v_mfma_f32_16x16x32_bf16 v[16:19], v[152:155], v[218:221], 0
	v_mfma_f32_16x16x32_bf16 v[4:7], v[144:147], v[226:229], 0
	v_mfma_f32_16x16x32_bf16 v[0:3], v[152:155], v[226:229], 0
	v_mfma_f32_16x16x32_bf16 v[52:55], v[148:151], v[174:177], v[52:55]
	v_mfma_f32_16x16x32_bf16 v[48:51], v[166:169], v[174:177], v[48:51]
	v_mfma_f32_16x16x32_bf16 v[36:39], v[148:151], v[214:217], v[36:39]
	v_mfma_f32_16x16x32_bf16 v[32:35], v[166:169], v[214:217], v[32:35]
	v_mfma_f32_16x16x32_bf16 v[20:23], v[148:151], v[222:225], v[20:23]
	v_mfma_f32_16x16x32_bf16 v[16:19], v[166:169], v[222:225], v[16:19]
	v_mfma_f32_16x16x32_bf16 v[4:7], v[148:151], v[230:233], v[4:7]
	v_mfma_f32_16x16x32_bf16 v[0:3], v[166:169], v[230:233], v[0:3]
	s_barrier
	s_branch .Lmy_sp3
